# M1 RWKV pre-pass: all 128 lora-weight fragment loads issued before one wait (was one round trip per pair); M2 staging loads of a unit issued together
# speedup vs baseline: 1.0657x; 1.0136x over previous
; __device__ __forceinline__ unsigned cvt_pk_bf16(float lo, float hi) { unsigned r; asm("v_cvt_pk_bf16_f32 %0, %1, %2" : "=v"(r) : "v"(lo), "v"(hi)); return r; }
; __device__ __forceinline__ void phase_m1(PP P, int l, LAS unsigned char* lds, const Ids I) {
;     ...
;         for (int nt = 0; nt < 4; ++nt) { const int dd = hd * 64 + nt * 16 + l15;
;             w0v[nt] = P->in[I_W0][l * 512 + dd]; a0v[nt] = P->in[I_A0][l * 512 + dd]; kkv[nt] = P->in[I_KK][l * 512 + dd]; kav[nt] = P->in[I_KA][l * 512 + dd];
; #pragma unroll
;             for (int ks = 0; ks < 2; ++ks) { const float* wp = P->in[I_W2] + ((size_t)l * 64 + ks * 32 + quad * 8) * 512 + dd; const float* ap = P->in[I_A2] + ((size_t)l * 64 + ks * 32 + quad * 8) * 512 + dd; u32x4 pk;
;                 pk.x = cvt_pk_bf16(wp[0], wp[512]); pk.y = cvt_pk_bf16(wp[1024], wp[1536]); pk.z = cvt_pk_bf16(wp[2048], wp[2560]); pk.w = cvt_pk_bf16(wp[3072], wp[3584]); bfw[nt][ks] = __builtin_bit_cast(bf16x8, pk);
;                 pk.x = cvt_pk_bf16(ap[0], ap[512]); pk.y = cvt_pk_bf16(ap[1024], ap[1536]); pk.z = cvt_pk_bf16(ap[2048], ap[2560]); pk.w = cvt_pk_bf16(ap[3072], ap[3584]); bfa[nt][ks] = __builtin_bit_cast(bf16x8, pk); } }
.LBB0_224:
	v_writelane_b32 v254, s36, 50
	v_readfirstlane_b32 s0, v96
	s_load_dwordx8 s[4:11], s[88:89], 0xc8
	v_writelane_b32 v254, s37, 51
	s_andn2_b32 s0, s0, 63
	v_writelane_b32 v254, s42, 52
	v_or_b32_e32 v66, s0, v64
	v_ashrrev_i32_e32 v67, 31, v66
	v_writelane_b32 v254, s43, 53
	v_writelane_b32 v254, s47, 54
	v_lshlrev_b64 v[0:1], 2, v[66:67]
	s_waitcnt lgkmcnt(0)
	v_lshl_add_u64 v[8:9], s[6:7], 0, v[0:1]
	v_lshl_add_u64 v[10:11], s[10:11], 0, v[0:1]
	v_lshlrev_b32_e32 v0, 14, v65
	v_readlane_b32 s1, v254, 41
	s_movk_i32 s6, 0x2000
	s_movk_i32 s7, 0x3000
	v_lshl_or_b32 v144, s1, 17, v0
	v_lshl_add_u64 v[48:49], v[8:9], 0, v[144:145]
	global_load_dword v0, v[48:49], off
	global_load_dword v152, v[48:49], off offset:2048
	s_movk_i32 s1, 0x1000
	v_add_co_u32_e32 v54, vcc, s1, v48
	v_lshl_add_u64 v[52:53], v[10:11], 0, v[144:145]
	s_nop 0
	v_addc_co_u32_e32 v55, vcc, 0, v49, vcc
	v_add_co_u32_e32 v50, vcc, s6, v48
	v_or_b32_e32 v144, 0x10000, v144
	s_nop 0
	v_addc_co_u32_e32 v51, vcc, 0, v49, vcc
	v_add_co_u32_e32 v58, vcc, s7, v48
	v_lshl_add_u64 v[72:73], v[8:9], 0, v[144:145]
	s_nop 0
	v_addc_co_u32_e32 v59, vcc, 0, v49, vcc
	v_add_co_u32_e32 v62, vcc, s1, v52
	v_lshl_add_u64 v[60:61], v[10:11], 0, v[144:145]
	s_nop 0
	v_addc_co_u32_e32 v63, vcc, 0, v53, vcc
	v_add_co_u32_e32 v56, vcc, s6, v52
	s_movk_i32 s3, 0xb00
	s_nop 0
	v_addc_co_u32_e32 v57, vcc, 0, v53, vcc
	v_add_co_u32_e32 v68, vcc, s7, v52
	s_cmpk_lt_i32 s93, 0x420
	s_nop 0
	v_addc_co_u32_e32 v69, vcc, 0, v53, vcc
	v_add_co_u32_e32 v74, vcc, s1, v72
	global_load_dword v1, v[50:51], off offset:-4096
	global_load_dword v153, v[54:55], off offset:2048
	v_addc_co_u32_e32 v75, vcc, 0, v73, vcc
	v_add_co_u32_e32 v70, vcc, s6, v72
	global_load_dword v2, v[50:51], off
	global_load_dword v154, v[50:51], off offset:2048
	v_addc_co_u32_e32 v71, vcc, 0, v73, vcc
	v_add_co_u32_e32 v76, vcc, s7, v72
	global_load_dword v3, v[58:59], off
	global_load_dword v155, v[58:59], off offset:2048
	v_addc_co_u32_e32 v77, vcc, 0, v73, vcc
	v_add_co_u32_e32 v80, vcc, s1, v60
	global_load_dword v4, v[52:53], off
	global_load_dword v156, v[52:53], off offset:2048
	v_addc_co_u32_e32 v81, vcc, 0, v61, vcc
	v_add_co_u32_e32 v78, vcc, s6, v60
	global_load_dword v5, v[56:57], off offset:-4096
	global_load_dword v157, v[62:63], off offset:2048
	v_addc_co_u32_e32 v79, vcc, 0, v61, vcc
	v_add_co_u32_e32 v82, vcc, s7, v60
	global_load_dword v6, v[56:57], off
	global_load_dword v158, v[56:57], off offset:2048
	v_addc_co_u32_e32 v83, vcc, 0, v61, vcc
	global_load_dword v7, v[68:69], off
	global_load_dword v160, v[68:69], off offset:2048
	global_load_dword v8, v[72:73], off
	global_load_dword v159, v[72:73], off offset:2048
	global_load_dword v9, v[70:71], off offset:-4096
	global_load_dword v161, v[74:75], off offset:2048
	global_load_dword v10, v[70:71], off
	global_load_dword v162, v[70:71], off offset:2048
	global_load_dword v11, v[76:77], off
	global_load_dword v163, v[76:77], off offset:2048
	global_load_dword v12, v[60:61], off
	global_load_dword v164, v[60:61], off offset:2048
	global_load_dword v13, v[78:79], off offset:-4096
	global_load_dword v165, v[80:81], off offset:2048
	global_load_dword v14, v[78:79], off
	global_load_dword v166, v[78:79], off offset:2048
	global_load_dword v15, v[82:83], off
	global_load_dword v167, v[82:83], off offset:2048
	global_load_dword v16, v[48:49], off offset:64
	global_load_dword v168, v[48:49], off offset:2112
	global_load_dword v17, v[54:55], off offset:64
	global_load_dword v169, v[54:55], off offset:2112
	global_load_dword v18, v[50:51], off offset:64
	global_load_dword v170, v[50:51], off offset:2112
	global_load_dword v19, v[58:59], off offset:64
	global_load_dword v171, v[58:59], off offset:2112
	global_load_dword v20, v[52:53], off offset:64
	global_load_dword v172, v[52:53], off offset:2112
	global_load_dword v21, v[62:63], off offset:64
	global_load_dword v173, v[62:63], off offset:2112
	global_load_dword v22, v[56:57], off offset:64
	global_load_dword v176, v[56:57], off offset:2112
	global_load_dword v23, v[68:69], off offset:64
	global_load_dword v177, v[68:69], off offset:2112
	global_load_dword v24, v[72:73], off offset:64
	global_load_dword v178, v[72:73], off offset:2112
	global_load_dword v25, v[74:75], off offset:64
	global_load_dword v179, v[74:75], off offset:2112
	global_load_dword v26, v[70:71], off offset:64
	global_load_dword v180, v[70:71], off offset:2112
	global_load_dword v27, v[76:77], off offset:64
	global_load_dword v181, v[76:77], off offset:2112
	global_load_dword v28, v[60:61], off offset:64
	global_load_dword v182, v[60:61], off offset:2112
	global_load_dword v29, v[80:81], off offset:64
	global_load_dword v183, v[80:81], off offset:2112
	global_load_dword v30, v[78:79], off offset:64
	global_load_dword v187, v[78:79], off offset:2112
	global_load_dword v31, v[82:83], off offset:64
	global_load_dword v188, v[82:83], off offset:2112
	global_load_dword v32, v[48:49], off offset:128
	global_load_dword v189, v[48:49], off offset:2176
	global_load_dword v33, v[54:55], off offset:128
	global_load_dword v190, v[54:55], off offset:2176
	global_load_dword v34, v[50:51], off offset:128
	global_load_dword v191, v[50:51], off offset:2176
	global_load_dword v35, v[58:59], off offset:128
	global_load_dword v192, v[58:59], off offset:2176
	global_load_dword v36, v[52:53], off offset:128
	global_load_dword v193, v[52:53], off offset:2176
	global_load_dword v37, v[62:63], off offset:128
	global_load_dword v194, v[62:63], off offset:2176
	global_load_dword v38, v[56:57], off offset:128
	global_load_dword v195, v[56:57], off offset:2176
; __device__ __forceinline__ unsigned cvt_pk_bf16(float lo, float hi) { unsigned r; asm("v_cvt_pk_bf16_f32 %0, %1, %2" : "=v"(r) : "v"(lo), "v"(hi)); return r; }
; __device__ __forceinline__ void phase_m1(PP P, int l, LAS unsigned char* lds, const Ids I) {
;     ...
;         for (int nt = 0; nt < 4; ++nt) { const int dd = hd * 64 + nt * 16 + l15;
;             w0v[nt] = P->in[I_W0][l * 512 + dd]; a0v[nt] = P->in[I_A0][l * 512 + dd]; kkv[nt] = P->in[I_KK][l * 512 + dd]; kav[nt] = P->in[I_KA][l * 512 + dd];
; #pragma unroll
;             for (int ks = 0; ks < 2; ++ks) { const float* wp = P->in[I_W2] + ((size_t)l * 64 + ks * 32 + quad * 8) * 512 + dd; const float* ap = P->in[I_A2] + ((size_t)l * 64 + ks * 32 + quad * 8) * 512 + dd; u32x4 pk;
;                 pk.x = cvt_pk_bf16(wp[0], wp[512]); pk.y = cvt_pk_bf16(wp[1024], wp[1536]); pk.z = cvt_pk_bf16(wp[2048], wp[2560]); pk.w = cvt_pk_bf16(wp[3072], wp[3584]); bfw[nt][ks] = __builtin_bit_cast(bf16x8, pk);
;                 pk.x = cvt_pk_bf16(ap[0], ap[512]); pk.y = cvt_pk_bf16(ap[1024], ap[1536]); pk.z = cvt_pk_bf16(ap[2048], ap[2560]); pk.w = cvt_pk_bf16(ap[3072], ap[3584]); bfa[nt][ks] = __builtin_bit_cast(bf16x8, pk); } }
	global_load_dword v39, v[68:69], off offset:128
	global_load_dword v196, v[68:69], off offset:2176
	global_load_dword v40, v[72:73], off offset:128
	global_load_dword v197, v[72:73], off offset:2176
	global_load_dword v41, v[74:75], off offset:128
	global_load_dword v198, v[74:75], off offset:2176
	global_load_dword v42, v[70:71], off offset:128
	global_load_dword v199, v[70:71], off offset:2176
	global_load_dword v43, v[76:77], off offset:128
	global_load_dword v200, v[76:77], off offset:2176
	global_load_dword v44, v[60:61], off offset:128
	global_load_dword v201, v[60:61], off offset:2176
	global_load_dword v45, v[80:81], off offset:128
	global_load_dword v202, v[80:81], off offset:2176
	global_load_dword v46, v[78:79], off offset:128
	global_load_dword v203, v[78:79], off offset:2176
	global_load_dword v47, v[82:83], off offset:128
	global_load_dword v204, v[82:83], off offset:2176
	global_load_dword v206, v[48:49], off offset:192
	s_nop 0
	global_load_dword v48, v[48:49], off offset:2240
	s_nop 0
	global_load_dword v49, v[54:55], off offset:192
	s_nop 0
	global_load_dword v205, v[54:55], off offset:2240
	global_load_dword v207, v[50:51], off offset:192
	s_nop 0
	global_load_dword v50, v[50:51], off offset:2240
	global_load_dword v51, v[58:59], off offset:192
	global_load_dword v208, v[58:59], off offset:2240
	global_load_dword v209, v[52:53], off offset:192
	s_nop 0
	global_load_dword v52, v[52:53], off offset:2240
	global_load_dword v53, v[62:63], off offset:192
	global_load_dword v210, v[62:63], off offset:2240
	global_load_dword v54, v[56:57], off offset:192
	global_load_dword v211, v[56:57], off offset:2240
	global_load_dword v55, v[68:69], off offset:192
	global_load_dword v212, v[68:69], off offset:2240
	global_load_dword v56, v[72:73], off offset:192
	global_load_dword v213, v[72:73], off offset:2240
	global_load_dword v57, v[74:75], off offset:192
	global_load_dword v214, v[74:75], off offset:2240
	global_load_dword v58, v[70:71], off offset:192
	global_load_dword v215, v[70:71], off offset:2240
	global_load_dword v59, v[76:77], off offset:192
	global_load_dword v216, v[76:77], off offset:2240
	global_load_dword v217, v[60:61], off offset:192
	s_nop 0
	global_load_dword v60, v[60:61], off offset:2240
	global_load_dword v61, v[80:81], off offset:192
	global_load_dword v218, v[80:81], off offset:2240
	global_load_dword v62, v[78:79], off offset:192
	global_load_dword v219, v[78:79], off offset:2240
	global_load_dword v63, v[82:83], off offset:192
	global_load_dword v67, v[82:83], off offset:2240
	s_waitcnt vmcnt(0)
	v_cvt_pk_bf16_f32 v0, v0, v152
	v_cvt_pk_bf16_f32 v1, v1, v153
	v_cvt_pk_bf16_f32 v2, v2, v154
	v_cvt_pk_bf16_f32 v3, v3, v155
	v_cvt_pk_bf16_f32 v4, v4, v156
	v_cvt_pk_bf16_f32 v5, v5, v157
	v_cvt_pk_bf16_f32 v6, v6, v158
	v_cvt_pk_bf16_f32 v8, v8, v159
	v_cvt_pk_bf16_f32 v7, v7, v160
	v_cvt_pk_bf16_f32 v9, v9, v161
	v_cvt_pk_bf16_f32 v10, v10, v162
	v_cvt_pk_bf16_f32 v11, v11, v163
	v_cvt_pk_bf16_f32 v12, v12, v164
	v_cvt_pk_bf16_f32 v13, v13, v165
	v_cvt_pk_bf16_f32 v14, v14, v166
	v_cvt_pk_bf16_f32 v15, v15, v167
	v_cvt_pk_bf16_f32 v16, v16, v168
	v_cvt_pk_bf16_f32 v17, v17, v169
	v_cvt_pk_bf16_f32 v18, v18, v170
	v_cvt_pk_bf16_f32 v19, v19, v171
	v_cvt_pk_bf16_f32 v20, v20, v172
	v_cvt_pk_bf16_f32 v21, v21, v173
	v_cvt_pk_bf16_f32 v22, v22, v176
	v_cvt_pk_bf16_f32 v23, v23, v177
	v_cvt_pk_bf16_f32 v24, v24, v178
	v_cvt_pk_bf16_f32 v25, v25, v179
	v_cvt_pk_bf16_f32 v26, v26, v180
	v_cvt_pk_bf16_f32 v27, v27, v181
	v_cvt_pk_bf16_f32 v28, v28, v182
	v_cvt_pk_bf16_f32 v29, v29, v183
	v_cvt_pk_bf16_f32 v30, v30, v187
	v_cvt_pk_bf16_f32 v31, v31, v188
	v_cvt_pk_bf16_f32 v32, v32, v189
	v_cvt_pk_bf16_f32 v33, v33, v190
	v_cvt_pk_bf16_f32 v34, v34, v191
	v_cvt_pk_bf16_f32 v35, v35, v192
	v_cvt_pk_bf16_f32 v36, v36, v193
	v_cvt_pk_bf16_f32 v37, v37, v194
	v_cvt_pk_bf16_f32 v38, v38, v195
	v_cvt_pk_bf16_f32 v39, v39, v196
	v_cvt_pk_bf16_f32 v40, v40, v197
	v_cvt_pk_bf16_f32 v41, v41, v198
	v_cvt_pk_bf16_f32 v42, v42, v199
	v_cvt_pk_bf16_f32 v43, v43, v200
	v_cvt_pk_bf16_f32 v44, v44, v201
	v_cvt_pk_bf16_f32 v45, v45, v202
	v_cvt_pk_bf16_f32 v46, v46, v203
	v_cvt_pk_bf16_f32 v47, v47, v204
	v_cvt_pk_bf16_f32 v49, v49, v205
	v_cvt_pk_bf16_f32 v48, v206, v48
	v_cvt_pk_bf16_f32 v50, v207, v50
	v_cvt_pk_bf16_f32 v51, v51, v208
	v_cvt_pk_bf16_f32 v52, v209, v52
	v_cvt_pk_bf16_f32 v53, v53, v210
	v_cvt_pk_bf16_f32 v54, v54, v211
	v_cvt_pk_bf16_f32 v55, v55, v212
	v_cvt_pk_bf16_f32 v56, v56, v213
	v_cvt_pk_bf16_f32 v57, v57, v214
	v_cvt_pk_bf16_f32 v58, v58, v215
	v_cvt_pk_bf16_f32 v59, v59, v216
	v_cvt_pk_bf16_f32 v60, v217, v60
	v_cvt_pk_bf16_f32 v61, v61, v218
	v_cvt_pk_bf16_f32 v62, v62, v219
	v_cvt_pk_bf16_f32 v63, v63, v67
	s_cbranch_scc0 .LBB0_318
; __device__ __forceinline__ void phase_m1(PP P, int l, LAS unsigned char* lds, const Ids I) {
;     ...
;         for (int nt = 0; nt < 4; ++nt) { const int dd = hd * 64 + nt * 16 + l15;
;             w0v[nt] = P->in[I_W0][l * 512 + dd]; a0v[nt] = P->in[I_A0][l * 512 + dd]; kkv[nt] = P->in[I_KK][l * 512 + dd]; kav[nt] = P->in[I_KA][l * 512 + dd];
;     ...
;         for (int u = BID; u < MT / 16; u += NB) {
;             const int r0 = u * 16;
; #pragma unroll
;             for (int it = 0; it < 7; ++it) { const int e = tid + 512 * it;
;                 if (e < 16 * 208) { const int tok = e / 208, col = (e - tok * 208) * 8, r = r0 + tok, t = t_in_seq(r);
	s_load_dwordx4 s[16:19], s[88:89], 0xf0
	v_readlane_b32 s1, v254, 47
	v_mul_u32_u24_e32 v64, 0x10e, v64
	s_mov_b32 s7, 0x4ec4ec4f
	v_add_u32_e32 v66, s1, v66
	v_ashrrev_i32_e32 v67, 31, v66
	v_lshlrev_b64 v[66:67], 2, v[66:67]
	v_lshl_add_u64 v[68:69], s[4:5], 0, v[66:67]
	v_lshl_add_u64 v[70:71], s[8:9], 0, v[66:67]
	s_load_dwordx2 s[4:5], s[88:89], 0xc0
	s_waitcnt lgkmcnt(0)
	v_lshl_add_u64 v[72:73], s[16:17], 0, v[66:67]
	v_lshl_add_u64 v[66:67], s[18:19], 0, v[66:67]
	global_load_dword v103, v[68:69], off
	global_load_dword v111, v[68:69], off offset:64
	global_load_dword v119, v[68:69], off offset:128
	global_load_dword v127, v[68:69], off offset:192
	global_load_dword v135, v[70:71], off
	global_load_dword v143, v[70:71], off offset:64
	global_load_dword v147, v[70:71], off offset:128
	global_load_dword v187, v[70:71], off offset:192
	global_load_dword v188, v[72:73], off
	global_load_dword v189, v[72:73], off offset:64
	global_load_dword v190, v[72:73], off offset:128
	global_load_dword v191, v[72:73], off offset:192
	global_load_dword v192, v[66:67], off
	global_load_dword v193, v[66:67], off offset:64
	global_load_dword v194, v[66:67], off offset:128
	global_load_dword v195, v[66:67], off offset:192
	v_lshlrev_b32_e32 v66, 4, v65
	v_add3_u32 v196, v85, v64, v66
	v_mul_hi_i32 v66, v96, s7
	v_readlane_b32 s1, v254, 42
	v_lshrrev_b32_e32 v67, 31, v66
	v_ashrrev_i32_e32 v66, 6, v66
	s_add_u32 s44, s4, s1
	v_lshl_add_u32 v70, s0, 1, v85
	s_movk_i32 s0, 0xd00
	v_add_u32_e32 v197, v66, v67
	s_movk_i32 s46, 0xff30
	s_addc_u32 s45, s5, 0
	v_cmp_gt_i32_e64 s[4:5], s0, v96
	v_mad_u64_u32 v[66:67], s[0:1], v197, s46, v[96:97]
	v_and_b32_e32 v67, -8, v66
	s_movk_i32 s47, 0xc0
	v_cmp_eq_u32_e64 s[0:1], s47, v67
	s_movk_i32 s50, 0xbf
	s_movk_i32 s6, 0x110
	v_writelane_b32 v254, s0, 55
	v_lshlrev_b32_e32 v98, 3, v66
	v_mul_lo_u32 v67, v197, s6
	v_writelane_b32 v254, s1, 56
	v_cmp_lt_i32_e64 s[0:1], s50, v66
	v_lshlrev_b32_e32 v66, 4, v66
	v_add3_u32 v102, 0, v67, v66
	v_add_u32_e32 v66, 0x200, v96
	v_writelane_b32 v254, s0, 57
	s_movk_i32 s51, 0xaf0
	v_mul_hi_i32 v67, v66, s7
	v_writelane_b32 v254, s1, 58
	v_lshrrev_b32_e32 v68, 31, v67
	v_ashrrev_i32_e32 v67, 6, v67
	v_ashrrev_i32_e32 v99, 31, v98
	v_and_b32_e32 v64, 0x1f8, v84
	v_lshl_add_u64 v[100:101], v[98:99], 2, s[44:45]
	v_lshlrev_b32_e32 v74, 12, v65
	v_lshl_add_u32 v71, v64, 1, 0
	v_ashrrev_i32_e32 v235, 6, v66
	v_cmp_gt_i32_e64 s[10:11], s3, v96
	v_lshl_add_u64 v[160:161], v[98:99], 1, s[60:61]
	s_lshl_b32 s54, s93, 4
	v_lshlrev_b32_e32 v241, 1, v64
	s_mov_b32 s90, s93
	s_waitcnt vmcnt(15)
	v_mad_u64_u32 v[104:105], s[0:1], v197, s51, v[102:103]
	v_add_u32_e32 v105, v67, v68
	v_mad_u64_u32 v[68:69], s[0:1], v105, s46, v[66:67]
	v_and_b32_e32 v67, -8, v68
	v_lshlrev_b32_e32 v106, 3, v68
	v_cmp_eq_u32_e64 s[0:1], s47, v67
	v_cmp_lt_i32_e64 s[8:9], s50, v68
	v_mul_lo_u32 v67, v105, s6
	v_lshlrev_b32_e32 v68, 4, v68
	v_add3_u32 v110, 0, v67, v68
	v_add_u32_e32 v68, 0x400, v96
	v_writelane_b32 v254, s0, 59
	v_mul_hi_i32 v67, v68, s7
	v_lshrrev_b32_e32 v69, 31, v67
	v_writelane_b32 v254, s1, 60
	s_waitcnt vmcnt(14)
	v_mad_u64_u32 v[112:113], s[0:1], v105, s51, v[110:111]
	v_ashrrev_i32_e32 v67, 6, v67
	s_movk_i32 s0, 0x900
	v_add_u32_e32 v113, v67, v69
	v_cmp_gt_i32_e64 s[16:17], s0, v96
	v_mad_u64_u32 v[68:69], s[0:1], v113, s46, v[68:69]
	v_and_b32_e32 v67, -8, v68
	v_lshlrev_b32_e32 v114, 3, v68
	v_cmp_eq_u32_e64 s[18:19], s47, v67
	v_cmp_lt_i32_e64 s[20:21], s50, v68
	v_mul_lo_u32 v67, v113, s6
	v_lshlrev_b32_e32 v68, 4, v68
	v_add3_u32 v118, 0, v67, v68
	v_add_u32_e32 v68, 0x600, v96
	v_mul_hi_i32 v67, v68, s7
	s_waitcnt vmcnt(13)
	v_mad_u64_u32 v[120:121], s[0:1], v113, s51, v[118:119]
	v_lshrrev_b32_e32 v69, 31, v67
	v_ashrrev_i32_e32 v67, 6, v67
	s_movk_i32 s0, 0x700
	v_add_u32_e32 v121, v67, v69
	v_cmp_gt_i32_e64 s[22:23], s0, v96
	v_mad_u64_u32 v[68:69], s[0:1], v121, s46, v[68:69]
	v_and_b32_e32 v67, -8, v68
	v_lshlrev_b32_e32 v122, 3, v68
	v_cmp_eq_u32_e64 s[24:25], s47, v67
	v_cmp_lt_i32_e64 s[26:27], s50, v68
	v_mul_lo_u32 v67, v121, s6
	v_lshlrev_b32_e32 v68, 4, v68
	v_add3_u32 v126, 0, v67, v68
	v_add_u32_e32 v68, 0x800, v96
	v_mul_hi_i32 v67, v68, s7
	s_waitcnt vmcnt(12)
; #define LAS __attribute__((address_space(3)))
; __device__ __forceinline__ unsigned cvt_pk_bf16(float lo, float hi) { unsigned r; asm("v_cvt_pk_bf16_f32 %0, %1, %2" : "=v"(r) : "v"(lo), "v"(hi)); return r; }
; __device__ __forceinline__ void phase_m1(PP P, int l, LAS unsigned char* lds, const Ids I) {
;     ...
;             for (int it = 0; it < 7; ++it) { const int e = tid + 512 * it;
;                 if (e < 16 * 208) { const int tok = e / 208, col = (e - tok * 208) * 8, r = r0 + tok, t = t_in_seq(r);
;                     float cf[8], pf[8]; unpack8(*(const u32x4*)(PR + (size_t)r * INW + 1024 + col), cf);
;                     if (t > 0) unpack8(*(const u32x4*)(PR + (size_t)(r - 1) * INW + 1024 + col), pf);
;                     else if (r < MTP) {
; #pragma unroll
;                         for (int j = 0; j < 8; ++j) pf[j] = 0.f; }
;                     else { const float* sp = P->in[I_SSHIFT] + ((size_t)l * 128 + ((r - MTP) >> 2)) * PW + col; const f32x4 s0 = *(const f32x4*)sp, s1 = *(const f32x4*)(sp + 4);
; #pragma unroll
;                         for (int j = 0; j < 4; ++j) { pf[j] = s0[j]; pf[4 + j] = s1[j]; } }
;                     const f32x4 m0 = *(const f32x4*)(mu + col), m1 = *(const f32x4*)(mu + col + 4); float xs[8];
; #pragma unroll
;                     for (int j = 0; j < 4; ++j) { xs[j] = cf[j] + (pf[j] - cf[j]) * m0[j]; xs[4 + j] = cf[4 + j] + (pf[4 + j] - cf[4 + j]) * m1[j]; }
;                     if (col >= 1536 && col < 1600) {
; #pragma unroll
;                         for (int j = 0; j < 8; ++j) xs[j] = tanh_f(xs[j]); }
;                     u32x4 w; w.x = cvt_pk_bf16(xs[0], xs[1]); w.y = cvt_pk_bf16(xs[2], xs[3]); w.z = cvt_pk_bf16(xs[4], xs[5]); w.w = cvt_pk_bf16(xs[6], xs[7]);
;                     if (col < 1536) *(LAS u32x4*)(XSB + tok * 1536 + col) = w; else *(LAS u32x4*)(AL + tok * 136 + (col - 1536)) = w; } }
;     ...
;                 for (int nt = 0; nt < 4; ++nt) { LAS bf16_t* ob = OR + tk * 512 + hd * 64 + nt * 16 + l15; const float kn = kk[nt] * rn;
;                     ob[0] = xp[nt * 16];
;                     ob[8192] = f2bf(0.60653066f * sigmoidf(w0v[nt] + aw[nt][j]));
;                     ob[2 * 8192] = f2bf(xk[nt] * (1.0f + (ar[nt] - 1.0f) * kav[nt]));
;                     ob[3 * 8192] = xp[1024 + nt * 16];
;                     ob[4 * 8192] = f2bf(kn); ob[5 * 8192] = f2bf(kn * ar[nt]); } }
	v_mad_u64_u32 v[128:129], s[0:1], v121, s51, v[126:127]
	v_lshrrev_b32_e32 v69, 31, v67
	v_ashrrev_i32_e32 v67, 6, v67
	s_movk_i32 s0, 0x500
	v_add_u32_e32 v129, v67, v69
	v_cmp_gt_i32_e64 s[28:29], s0, v96
	v_mad_u64_u32 v[68:69], s[0:1], v129, s46, v[68:69]
	v_and_b32_e32 v67, -8, v68
	v_lshlrev_b32_e32 v130, 3, v68
	v_cmp_eq_u32_e64 s[30:31], s47, v67
	v_cmp_lt_i32_e64 s[34:35], s50, v68
	v_mul_lo_u32 v67, v129, s6
	v_lshlrev_b32_e32 v68, 4, v68
	v_add3_u32 v134, 0, v67, v68
	v_add_u32_e32 v68, 0xa00, v96
	v_mul_hi_i32 v67, v68, s7
	s_waitcnt vmcnt(11)
	v_mad_u64_u32 v[136:137], s[0:1], v129, s51, v[134:135]
	v_lshrrev_b32_e32 v69, 31, v67
	v_ashrrev_i32_e32 v67, 6, v67
	s_movk_i32 s0, 0x300
	v_add_u32_e32 v137, v67, v69
	v_cmp_gt_i32_e64 s[36:37], s0, v96
	v_mad_u64_u32 v[68:69], s[0:1], v137, s46, v[68:69]
	v_and_b32_e32 v67, -8, v68
	v_lshlrev_b32_e32 v138, 3, v68
	v_cmp_eq_u32_e64 s[38:39], s47, v67
	v_cmp_lt_i32_e64 s[40:41], s50, v68
	v_mul_lo_u32 v67, v137, s6
	v_lshlrev_b32_e32 v68, 4, v68
	v_add3_u32 v142, 0, v67, v68
	v_add_u32_e32 v68, 0xc00, v96
	v_mul_hi_i32 v67, v68, s7
	s_waitcnt vmcnt(10)
	v_mad_u64_u32 v[152:153], s[0:1], v137, s51, v[142:143]
	v_lshrrev_b32_e32 v69, 31, v67
	v_ashrrev_i32_e32 v67, 6, v67
	s_movk_i32 s0, 0x100
	v_add_u32_e32 v153, v67, v69
	v_cmp_gt_i32_e64 s[42:43], s0, v96
	v_mad_u64_u32 v[68:69], s[0:1], v153, s46, v[68:69]
	v_lshlrev_b32_e32 v154, 3, v68
	v_ashrrev_i32_e32 v107, 31, v106
	v_ashrrev_i32_e32 v115, 31, v114
	v_ashrrev_i32_e32 v123, 31, v122
	v_ashrrev_i32_e32 v131, 31, v130
	v_ashrrev_i32_e32 v139, 31, v138
	v_ashrrev_i32_e32 v155, 31, v154
	v_and_b32_e32 v67, -8, v68
	v_lshl_add_u64 v[108:109], v[106:107], 2, s[44:45]
	v_lshl_add_u64 v[116:117], v[114:115], 2, s[44:45]
	v_lshl_add_u64 v[124:125], v[122:123], 2, s[44:45]
	v_lshl_add_u64 v[132:133], v[130:131], 2, s[44:45]
	v_lshl_add_u64 v[140:141], v[138:139], 2, s[44:45]
	v_lshl_add_u64 v[156:157], v[154:155], 2, s[44:45]
	v_cmp_eq_u32_e64 s[44:45], s47, v67
	v_cmp_lt_i32_e64 s[46:47], s50, v68
	v_mul_lo_u32 v67, v153, s6
	v_lshlrev_b32_e32 v68, 4, v68
	v_add3_u32 v144, 0, v67, v68
	v_mul_u32_u24_e32 v67, 0x3000, v65
	v_lshl_or_b32 v68, v65, 2, 1
	v_lshl_add_u32 v65, v65, 12, v70
	v_mad_u64_u32 v[158:159], s[0:1], v153, s51, v[144:145]
	v_add_u32_e32 v212, 0x800, v65
	v_add_u32_e32 v213, 0xd900, v65
	v_add_u32_e32 v214, 0x1d900, v65
	v_add_u32_e32 v215, 0x21900, v65
	v_add_u32_e32 v216, 0x1d920, v65
	v_add_u32_e32 v217, 0x21920, v65
	v_add_u32_e32 v218, 0x1d940, v65
	v_add_u32_e32 v219, 0x21940, v65
	v_add_u32_e32 v220, 0x1d960, v65
	v_add_u32_e32 v221, 0x21960, v65
	v_add_u32_e32 v222, 0xc00, v65
	v_add_u32_e32 v223, 0xdd00, v65
	v_add_u32_e32 v224, 0x1dd00, v65
	v_add_u32_e32 v225, 0x21d00, v65
	v_add_u32_e32 v226, 0x1dd20, v65
	v_add_u32_e32 v227, 0x21d20, v65
	v_add_u32_e32 v228, 0x1dd40, v65
	v_add_u32_e32 v229, 0x21d40, v65
	v_add_u32_e32 v230, 0x1dd60, v65
	v_add_u32_e32 v231, 0x21d60, v65
	v_lshl_add_u32 v65, v97, 10, v71
	v_add_u32_e32 v159, v70, v74
	v_mul_u32_u24_e32 v69, 0xc00, v68
	v_lshl_add_u32 v202, v68, 10, v70
	v_add_u32_e32 v232, 0xd100, v65
	v_add_u32_e32 v233, 0x1d100, v65
	v_add_u32_e32 v234, 0x21100, v65
	v_lshl_add_u32 v65, v235, 10, v71
	v_add_u32_e32 v198, 0xd100, v159
	v_add_u32_e32 v199, 0x21140, v159
	v_add_u32_e32 v200, 0x1d160, v159
	v_add_u32_e32 v201, 0x21160, v159
	v_add_u32_e32 v203, 0xd100, v202
	v_add_u32_e32 v204, 0x1d100, v202
	v_add_u32_e32 v205, 0x21100, v202
	v_add_u32_e32 v206, 0x1d120, v202
	v_add_u32_e32 v207, 0x21120, v202
	v_add_u32_e32 v208, 0x1d140, v202
	v_add_u32_e32 v209, 0x21140, v202
	v_add_u32_e32 v210, 0x1d160, v202
	v_add_u32_e32 v211, 0x21160, v202
	v_add_u32_e32 v236, 0xd100, v65
	v_add_u32_e32 v237, 0x1d100, v65
	v_add_u32_e32 v238, 0x21100, v65
	v_lshl_add_u64 v[162:163], v[106:107], 1, s[60:61]
	v_lshl_add_u64 v[164:165], v[114:115], 1, s[60:61]
	v_lshl_add_u64 v[166:167], v[122:123], 1, s[60:61]
	v_lshl_add_u64 v[168:169], v[130:131], 1, s[60:61]
	v_lshl_add_u64 v[170:171], v[138:139], 1, s[60:61]
	v_lshl_add_u64 v[172:173], v[154:155], 1, s[60:61]
	v_add_u32_e32 v239, v70, v67
	v_add_u32_e32 v240, v70, v69
	s_branch .LBB0_227

; #define LAS __attribute__((address_space(3)))
; __device__ __forceinline__ float bf2f(bf16_t h) { return __uint_as_float((unsigned)h << 16); }
; __device__ __forceinline__ bf16_t f2bf(float f) { return (bf16_t)(cvt_pk_bf16(f, 0.f) & 0xffffu); }
; __device__ __forceinline__ float sigmoidf(float x) { return rcpf(1.0f + __expf(-x)); }
; __device__ __forceinline__ void phase_m2(PP P, int l, LAS unsigned char* lds, const Ids I) {
;     ...
;         for (int i = 0; i < 3; ++i) { const int idx = tid + 512 * i; if (idx < 11 * 128) { const int tok = idx >> 7, col = idx & 127, r = r0 + tok, t = t_in_seq(r);
;             const float cur = bf2f(PR[(size_t)r * INW + 2688 + col]);
;             const float prev = t > 0 ? bf2f(PR[(size_t)(r - 1) * INW + 2688 + col]) : (r < MTP ? 0.f : P->in[I_SSHIFT][((size_t)l * 128 + ((r - MTP) >> 2)) * PW + 1664 + col]);
;             const float sg = sigmoidf(cur + (prev - cur) * mu[1664 + col]); const bf16_t h = f2bf(sg);
;             SGH[tok * 136 + col] = h; SGL[tok * 136 + col] = f2bf(sg - bf2f(h)); } }
; #pragma unroll
;         for (int i = 0; i < 2; ++i) { const int idx = tid + 512 * i; if (idx < 11 * 64) { const int tok = idx >> 6, c8 = (idx & 63) * 8; const size_t r = (size_t)r0 + tok; float f[8];
;             unpack8(*(const u32x4*)(ymix + r * 1024 + 512 + c8), f); *(LAS f32x4*)(LY + tok * 512 + c8) = (f32x4){f[0], f[1], f[2], f[3]}; *(LAS f32x4*)(LY + tok * 512 + c8 + 4) = (f32x4){f[4], f[5], f[6], f[7]};
;             unpack8(*(const u32x4*)(arr + A_R * AS + r * 512 + c8), f); *(LAS f32x4*)(LR + tok * 512 + c8) = (f32x4){f[0], f[1], f[2], f[3]}; *(LAS f32x4*)(LR + tok * 512 + c8 + 4) = (f32x4){f[4], f[5], f[6], f[7]};
;             unpack8(*(const u32x4*)(arr + A_KF * AS + r * 512 + c8), f); *(LAS f32x4*)(LK + tok * 512 + c8) = (f32x4){f[0], f[1], f[2], f[3]}; *(LAS f32x4*)(LK + tok * 512 + c8 + 4) = (f32x4){f[4], f[5], f[6], f[7]};
;             unpack8(*(const u32x4*)(arr + A_V * AS + r * 512 + c8), f); *(LAS f32x4*)(LV + tok * 512 + c8) = (f32x4){f[0], f[1], f[2], f[3]}; *(LAS f32x4*)(LV + tok * 512 + c8 + 4) = (f32x4){f[4], f[5], f[6], f[7]}; } }
.LBB0_433:
	s_mul_i32 s0, s3, 11
	v_lshlrev_b32_e32 v144, 1, v154
	s_load_dwordx2 s[22:23], s[88:89], 0x30
	s_ashr_i32 s1, s0, 31
	global_load_dword v224, v[156:157], off
	s_add_u32 s24, s60, 0x1500
	s_addc_u32 s25, s61, 0
	v_mov_b64_e32 v[210:211], s[24:25]
	v_lshlrev_b32_e32 v209, 2, v154
	s_waitcnt lgkmcnt(0)
	s_add_u32 s22, s22, 0x1a00
	s_addc_u32 s23, s23, 0
	s_movk_i32 s24, 0x1c00
	s_mov_b64 exec, s[4:5]
	v_add_u32_e32 v212, s0, v188
	v_mad_i64_i32 v[204:205], s[26:27], v212, s73, v[210:211]
	v_add_u32_e32 v208, -1, v212
	v_lshl_add_u64 v[204:205], v[204:205], 0, v[144:145]
	v_mad_i64_i32 v[206:207], s[26:27], v208, s73, v[210:211]
	global_load_ushort v215, v[204:205], off
	v_lshl_add_u64 v[206:207], v[206:207], 0, v[144:145]
	v_mov_b32_e32 v221, 0
	global_load_ushort v218, v[206:207], off
	v_and_b32_e32 v208, 3, v212
	v_cmp_lt_i32_e32 vcc, s76, v212
	v_cmp_eq_u32_e64 s[26:27], 0, v208
	s_and_b64 s[26:27], vcc, s[26:27]
	s_and_saveexec_b64 s[28:29], s[26:27]
	v_add_u32_e32 v208, 0xffffc000, v212
	v_lshrrev_b32_e32 v208, 2, v208
	v_add_u32_e32 v208, s34, v208
	v_mov_b64_e32 v[206:207], s[22:23]
	v_mad_u64_u32 v[206:207], s[26:27], v208, s24, v[206:207]
	v_mov_b32_e32 v205, v145
	v_mov_b32_e32 v204, v209
	v_lshl_add_u64 v[206:207], v[206:207], 0, v[204:205]
	global_load_dword v221, v[206:207], off
	s_mov_b64 exec, s[6:7]
	v_add_u32_e32 v213, s0, v190
	v_mad_i64_i32 v[204:205], s[26:27], v213, s73, v[210:211]
	v_add_u32_e32 v208, -1, v213
	v_lshl_add_u64 v[204:205], v[204:205], 0, v[144:145]
	v_mad_i64_i32 v[206:207], s[26:27], v208, s73, v[210:211]
	global_load_ushort v216, v[204:205], off
	v_lshl_add_u64 v[206:207], v[206:207], 0, v[144:145]
	v_mov_b32_e32 v222, 0
	global_load_ushort v219, v[206:207], off
	v_and_b32_e32 v208, 3, v213
	v_cmp_lt_i32_e32 vcc, s76, v213
	v_cmp_eq_u32_e64 s[26:27], 0, v208
	s_and_b64 s[26:27], vcc, s[26:27]
	s_and_saveexec_b64 s[28:29], s[26:27]
	v_add_u32_e32 v208, 0xffffc000, v213
	v_lshrrev_b32_e32 v208, 2, v208
	v_add_u32_e32 v208, s34, v208
	v_mov_b64_e32 v[206:207], s[22:23]
	v_mad_u64_u32 v[206:207], s[26:27], v208, s24, v[206:207]
	v_mov_b32_e32 v205, v145
	v_mov_b32_e32 v204, v209
	v_lshl_add_u64 v[206:207], v[206:207], 0, v[204:205]
	global_load_dword v222, v[206:207], off
	s_mov_b64 exec, s[8:9]
	v_add_u32_e32 v214, s0, v192
	v_mad_i64_i32 v[204:205], s[26:27], v214, s73, v[210:211]
	v_add_u32_e32 v208, -1, v214
	v_lshl_add_u64 v[204:205], v[204:205], 0, v[144:145]
	v_mad_i64_i32 v[206:207], s[26:27], v208, s73, v[210:211]
	global_load_ushort v217, v[204:205], off
	v_lshl_add_u64 v[206:207], v[206:207], 0, v[144:145]
	v_mov_b32_e32 v223, 0
	global_load_ushort v220, v[206:207], off
	v_and_b32_e32 v208, 3, v214
	v_cmp_lt_i32_e32 vcc, s76, v214
	v_cmp_eq_u32_e64 s[26:27], 0, v208
	s_and_b64 s[26:27], vcc, s[26:27]
	s_and_saveexec_b64 s[28:29], s[26:27]
	v_add_u32_e32 v208, 0xffffc000, v214
	v_lshrrev_b32_e32 v208, 2, v208
	v_add_u32_e32 v208, s34, v208
	v_mov_b64_e32 v[206:207], s[22:23]
	v_mad_u64_u32 v[206:207], s[26:27], v208, s24, v[206:207]
	v_mov_b32_e32 v205, v145
	v_mov_b32_e32 v204, v209
	v_lshl_add_u64 v[206:207], v[206:207], 0, v[204:205]
	global_load_dword v223, v[206:207], off
	s_mov_b64 exec, -1
	v_lshl_add_u64 v[204:205], s[0:1], 0, v[164:165]
	v_lshlrev_b64 v[170:171], 11, v[204:205]
	s_mov_b64 exec, s[10:11]
	v_lshl_add_u64 v[206:207], v[168:169], 0, v[170:171]
	v_lshlrev_b64 v[204:205], 10, v[204:205]
	global_load_dwordx4 v[128:131], v[206:207], off offset:1024
	v_lshl_add_u64 v[206:207], v[158:159], 0, v[204:205]
	global_load_dwordx4 v[132:135], v[206:207], off
	v_lshl_add_u64 v[206:207], v[160:161], 0, v[204:205]
	global_load_dwordx4 v[136:139], v[206:207], off
	v_lshl_add_u64 v[206:207], v[162:163], 0, v[204:205]
	global_load_dwordx4 v[140:143], v[206:207], off
	s_mov_b64 exec, -1
	v_lshl_add_u64 v[204:205], s[0:1], 0, v[166:167]
	v_lshlrev_b64 v[172:173], 11, v[204:205]
	s_mov_b64 exec, s[12:13]
	v_lshl_add_u64 v[206:207], v[168:169], 0, v[172:173]
	v_lshlrev_b64 v[204:205], 10, v[204:205]
	global_load_dwordx4 v[176:179], v[206:207], off offset:1024
	v_lshl_add_u64 v[206:207], v[158:159], 0, v[204:205]
	global_load_dwordx4 v[180:183], v[206:207], off
	v_lshl_add_u64 v[206:207], v[160:161], 0, v[204:205]
	global_load_dwordx4 v[226:229], v[206:207], off
	v_lshl_add_u64 v[206:207], v[162:163], 0, v[204:205]
	global_load_dwordx4 v[230:233], v[206:207], off
	s_mov_b64 exec, -1
	s_waitcnt vmcnt(0)
; #define LAS __attribute__((address_space(3)))
; __device__ __forceinline__ float bf2f(bf16_t h) { return __uint_as_float((unsigned)h << 16); }
; __device__ __forceinline__ bf16_t f2bf(float f) { return (bf16_t)(cvt_pk_bf16(f, 0.f) & 0xffffu); }
; __device__ __forceinline__ float sigmoidf(float x) { return rcpf(1.0f + __expf(-x)); }
; __device__ __forceinline__ void phase_m2(PP P, int l, LAS unsigned char* lds, const Ids I) {
;     ...
;         for (int i = 0; i < 3; ++i) { const int idx = tid + 512 * i; if (idx < 11 * 128) { const int tok = idx >> 7, col = idx & 127, r = r0 + tok, t = t_in_seq(r);
;             const float cur = bf2f(PR[(size_t)r * INW + 2688 + col]);
;             const float prev = t > 0 ? bf2f(PR[(size_t)(r - 1) * INW + 2688 + col]) : (r < MTP ? 0.f : P->in[I_SSHIFT][((size_t)l * 128 + ((r - MTP) >> 2)) * PW + 1664 + col]);
;             const float sg = sigmoidf(cur + (prev - cur) * mu[1664 + col]); const bf16_t h = f2bf(sg);
;             SGH[tok * 136 + col] = h; SGL[tok * 136 + col] = f2bf(sg - bf2f(h)); } }
; #pragma unroll
;         for (int i = 0; i < 2; ++i) { const int idx = tid + 512 * i; if (idx < 11 * 64) { const int tok = idx >> 6, c8 = (idx & 63) * 8; const size_t r = (size_t)r0 + tok; float f[8];
;             unpack8(*(const u32x4*)(ymix + r * 1024 + 512 + c8), f); *(LAS f32x4*)(LY + tok * 512 + c8) = (f32x4){f[0], f[1], f[2], f[3]}; *(LAS f32x4*)(LY + tok * 512 + c8 + 4) = (f32x4){f[4], f[5], f[6], f[7]};
;             unpack8(*(const u32x4*)(arr + A_R * AS + r * 512 + c8), f); *(LAS f32x4*)(LR + tok * 512 + c8) = (f32x4){f[0], f[1], f[2], f[3]}; *(LAS f32x4*)(LR + tok * 512 + c8 + 4) = (f32x4){f[4], f[5], f[6], f[7]};
;             unpack8(*(const u32x4*)(arr + A_KF * AS + r * 512 + c8), f); *(LAS f32x4*)(LK + tok * 512 + c8) = (f32x4){f[0], f[1], f[2], f[3]}; *(LAS f32x4*)(LK + tok * 512 + c8 + 4) = (f32x4){f[4], f[5], f[6], f[7]};
;             unpack8(*(const u32x4*)(arr + A_V * AS + r * 512 + c8), f); *(LAS f32x4*)(LV + tok * 512 + c8) = (f32x4){f[0], f[1], f[2], f[3]}; *(LAS f32x4*)(LV + tok * 512 + c8 + 4) = (f32x4){f[4], f[5], f[6], f[7]}; } }
;         __syncthreads();
	s_mov_b64 exec, s[4:5]
	v_cmp_gt_i32_e32 vcc, s91, v212
	v_lshlrev_b32_e32 v215, 16, v215
	v_lshlrev_b32_e32 v218, 16, v218
	v_cndmask_b32_e32 v208, 3, v185, vcc
	v_and_b32_e32 v208, v208, v212
	v_cmp_ne_u32_e32 vcc, 0, v208
	s_nop 1
	v_cndmask_b32_e32 v218, v221, v218, vcc
	v_sub_f32_e32 v208, v218, v215
	v_fmac_f32_e32 v215, v208, v224
	v_mul_f32_e32 v215, 0xbfb8aa3b, v215
	v_exp_f32_e32 v215, v215
	s_nop 0
	v_add_f32_e32 v215, 1.0, v215
	v_rcp_f32_e32 v215, v215
	s_nop 0
	v_cvt_pk_bf16_f32 v208, v215, v145
	ds_write_b16 v189, v208
	v_lshlrev_b32_e32 v218, 16, v208
	v_sub_f32_e32 v215, v215, v218
	v_cvt_pk_bf16_f32 v215, v215, v145
	ds_write_b16 v189, v215 offset:4352
	s_mov_b64 exec, s[6:7]
	v_cmp_gt_i32_e32 vcc, s91, v213
	v_lshlrev_b32_e32 v216, 16, v216
	v_lshlrev_b32_e32 v219, 16, v219
	v_cndmask_b32_e32 v208, 3, v185, vcc
	v_and_b32_e32 v208, v208, v213
	v_cmp_ne_u32_e32 vcc, 0, v208
	s_nop 1
	v_cndmask_b32_e32 v219, v222, v219, vcc
	v_sub_f32_e32 v208, v219, v216
	v_fmac_f32_e32 v216, v208, v224
	v_mul_f32_e32 v216, 0xbfb8aa3b, v216
	v_exp_f32_e32 v216, v216
	s_nop 0
	v_add_f32_e32 v216, 1.0, v216
	v_rcp_f32_e32 v216, v216
	s_nop 0
	v_cvt_pk_bf16_f32 v208, v216, v145
	ds_write_b16 v191, v208
	v_lshlrev_b32_e32 v219, 16, v208
	v_sub_f32_e32 v216, v216, v219
	v_cvt_pk_bf16_f32 v216, v216, v145
	ds_write_b16 v191, v216 offset:4352
	s_mov_b64 exec, s[8:9]
	v_cmp_gt_i32_e32 vcc, s91, v214
	v_lshlrev_b32_e32 v217, 16, v217
	v_lshlrev_b32_e32 v220, 16, v220
	v_cndmask_b32_e32 v208, 3, v185, vcc
	v_and_b32_e32 v208, v208, v214
	v_cmp_ne_u32_e32 vcc, 0, v208
	s_nop 1
	v_cndmask_b32_e32 v220, v223, v220, vcc
	v_sub_f32_e32 v208, v220, v217
	v_fmac_f32_e32 v217, v208, v224
	v_mul_f32_e32 v217, 0xbfb8aa3b, v217
	v_exp_f32_e32 v217, v217
	s_nop 0
	v_add_f32_e32 v217, 1.0, v217
	v_rcp_f32_e32 v217, v217
	s_nop 0
	v_cvt_pk_bf16_f32 v208, v217, v145
	ds_write_b16 v193, v208
	v_lshlrev_b32_e32 v220, 16, v208
	v_sub_f32_e32 v217, v217, v220
	v_cvt_pk_bf16_f32 v217, v217, v145
	ds_write_b16 v193, v217 offset:4352
	s_mov_b64 exec, s[10:11]
	v_lshlrev_b32_e32 v242, 16, v128
	v_and_b32_e32 v243, 0xffff0000, v128
	v_lshlrev_b32_e32 v244, 16, v129
	v_and_b32_e32 v245, 0xffff0000, v129
	v_lshlrev_b32_e32 v246, 16, v130
	v_and_b32_e32 v247, 0xffff0000, v130
	v_lshlrev_b32_e32 v248, 16, v131
	v_and_b32_e32 v249, 0xffff0000, v131
	ds_write_b128 v194, v[242:245] offset:8704
	ds_write_b128 v194, v[246:249] offset:8720
	v_lshlrev_b32_e32 v250, 16, v132
	v_and_b32_e32 v251, 0xffff0000, v132
	v_lshlrev_b32_e32 v252, 16, v133
	v_and_b32_e32 v253, 0xffff0000, v133
	v_lshlrev_b32_e32 v204, 16, v134
	v_and_b32_e32 v205, 0xffff0000, v134
	v_lshlrev_b32_e32 v206, 16, v135
	v_and_b32_e32 v207, 0xffff0000, v135
	ds_write_b128 v194, v[250:253] offset:31232
	ds_write_b128 v194, v[204:207] offset:31248
	v_lshlrev_b32_e32 v242, 16, v136
	v_and_b32_e32 v243, 0xffff0000, v136
	v_lshlrev_b32_e32 v244, 16, v137
	v_and_b32_e32 v245, 0xffff0000, v137
	v_lshlrev_b32_e32 v246, 16, v138
	v_and_b32_e32 v247, 0xffff0000, v138
	v_lshlrev_b32_e32 v248, 16, v139
	v_and_b32_e32 v249, 0xffff0000, v139
	ds_write_b128 v194, v[242:245] offset:53760
	ds_write_b128 v194, v[246:249] offset:53776
	v_lshlrev_b32_e32 v250, 16, v140
	v_and_b32_e32 v251, 0xffff0000, v140
	v_lshlrev_b32_e32 v252, 16, v141
	v_and_b32_e32 v253, 0xffff0000, v141
	v_lshlrev_b32_e32 v204, 16, v142
	v_and_b32_e32 v205, 0xffff0000, v142
	v_lshlrev_b32_e32 v206, 16, v143
	v_and_b32_e32 v207, 0xffff0000, v143
	ds_write_b128 v195, v[250:253]
	ds_write_b128 v195, v[204:207] offset:16
	s_mov_b64 exec, s[12:13]
	v_lshlrev_b32_e32 v242, 16, v176
	v_and_b32_e32 v243, 0xffff0000, v176
	v_lshlrev_b32_e32 v244, 16, v177
	v_and_b32_e32 v245, 0xffff0000, v177
	v_lshlrev_b32_e32 v246, 16, v178
	v_and_b32_e32 v247, 0xffff0000, v178
	v_lshlrev_b32_e32 v248, 16, v179
	v_and_b32_e32 v249, 0xffff0000, v179
	ds_write_b128 v196, v[242:245] offset:8704
	ds_write_b128 v196, v[246:249] offset:8720
	v_lshlrev_b32_e32 v250, 16, v180
	v_and_b32_e32 v251, 0xffff0000, v180
	v_lshlrev_b32_e32 v252, 16, v181
	v_and_b32_e32 v253, 0xffff0000, v181
	v_lshlrev_b32_e32 v204, 16, v182
	v_and_b32_e32 v205, 0xffff0000, v182
	v_lshlrev_b32_e32 v206, 16, v183
	v_and_b32_e32 v207, 0xffff0000, v183
	ds_write_b128 v196, v[250:253] offset:31232
	ds_write_b128 v196, v[204:207] offset:31248
	v_lshlrev_b32_e32 v242, 16, v226
	v_and_b32_e32 v243, 0xffff0000, v226
	v_lshlrev_b32_e32 v244, 16, v227
	v_and_b32_e32 v245, 0xffff0000, v227
	v_lshlrev_b32_e32 v246, 16, v228
	v_and_b32_e32 v247, 0xffff0000, v228
	v_lshlrev_b32_e32 v248, 16, v229
	v_and_b32_e32 v249, 0xffff0000, v229
	ds_write_b128 v196, v[242:245] offset:53760
	ds_write_b128 v196, v[246:249] offset:53776
	v_lshlrev_b32_e32 v250, 16, v230
	v_and_b32_e32 v251, 0xffff0000, v230
	v_lshlrev_b32_e32 v252, 16, v231
	v_and_b32_e32 v253, 0xffff0000, v231
	v_lshlrev_b32_e32 v204, 16, v232
	v_and_b32_e32 v205, 0xffff0000, v232
	v_lshlrev_b32_e32 v206, 16, v233
	v_and_b32_e32 v207, 0xffff0000, v233
	ds_write_b128 v197, v[250:253]
	ds_write_b128 v197, v[204:207] offset:16
	s_mov_b64 exec, -1
	s_waitcnt lgkmcnt(0)
	s_barrier
; #define LAS __attribute__((address_space(3)))
; __device__ __forceinline__ void phase_m2(PP P, int l, LAS unsigned char* lds, const Ids I) {
;     ...
;         { f32x4 ag[4];
; #pragma unroll
;           for (int nt = 0; nt < 4; ++nt) ag[nt] = (f32x4){0.f, 0.f, 0.f, 0.f};
; #pragma unroll
;           for (int ks = 0; ks < 4; ++ks) { const bf16x8 fh = *(const LAS bf16x8*)(SGH + l15 * 136 + ks * 32 + quad * 8), fl = *(const LAS bf16x8*)(SGL + l15 * 136 + ks * 32 + quad * 8);
; #pragma unroll
;               for (int nt = 0; nt < 4; ++nt) { ag[nt] = __builtin_amdgcn_mfma_f32_16x16x32_bf16(fl, bfh[nt][ks], ag[nt], 0, 0, 0); ag[nt] = __builtin_amdgcn_mfma_f32_16x16x32_bf16(fh, bfl[nt][ks], ag[nt], 0, 0, 0);
;                   ag[nt] = __builtin_amdgcn_mfma_f32_16x16x32_bf16(fh, bfh[nt][ks], ag[nt], 0, 0, 0); } }
; #pragma unroll
;           for (int nt = 0; nt < 4; ++nt)
; #pragma unroll
;               for (int j = 0; j < 4; ++j) if (quad * 4 + j < 11) G[(quad * 4 + j) * 512 + hd * 64 + nt * 16 + l15] = ag[nt][j]; }
	ds_read_b128 v[128:131], v187
	ds_read_b128 v[132:135], v187 offset:4352
	s_waitcnt lgkmcnt(0)
	v_mfma_f32_16x16x32_bf16 v[136:139], v[132:135], v[0:3], 0
	v_mfma_f32_16x16x32_bf16 v[140:143], v[132:135], v[32:35], 0
	v_mfma_f32_16x16x32_bf16 v[176:179], v[132:135], v[64:67], 0
	v_mfma_f32_16x16x32_bf16 v[132:135], v[132:135], v[96:99], 0
	v_mfma_f32_16x16x32_bf16 v[136:139], v[128:131], v[4:7], v[136:139]
	v_mfma_f32_16x16x32_bf16 v[140:143], v[128:131], v[36:39], v[140:143]
	v_mfma_f32_16x16x32_bf16 v[176:179], v[128:131], v[68:71], v[176:179]
	v_mfma_f32_16x16x32_bf16 v[132:135], v[128:131], v[100:103], v[132:135]
	v_mfma_f32_16x16x32_bf16 v[136:139], v[128:131], v[0:3], v[136:139]
	v_mfma_f32_16x16x32_bf16 v[140:143], v[128:131], v[32:35], v[140:143]
	v_mfma_f32_16x16x32_bf16 v[176:179], v[128:131], v[64:67], v[176:179]
	v_mfma_f32_16x16x32_bf16 v[128:131], v[128:131], v[96:99], v[132:135]
	s_nop 3
	ds_read_b128 v[132:135], v187 offset:64
	ds_read_b128 v[180:183], v187 offset:4416
	s_waitcnt lgkmcnt(0)
	v_mfma_f32_16x16x32_bf16 v[136:139], v[180:183], v[8:11], v[136:139]
	v_mfma_f32_16x16x32_bf16 v[140:143], v[180:183], v[40:43], v[140:143]
	v_mfma_f32_16x16x32_bf16 v[176:179], v[180:183], v[72:75], v[176:179]
	v_mfma_f32_16x16x32_bf16 v[128:131], v[180:183], v[104:107], v[128:131]
	v_mfma_f32_16x16x32_bf16 v[136:139], v[132:135], v[12:15], v[136:139]
	v_mfma_f32_16x16x32_bf16 v[140:143], v[132:135], v[44:47], v[140:143]
	v_mfma_f32_16x16x32_bf16 v[176:179], v[132:135], v[76:79], v[176:179]
	v_mfma_f32_16x16x32_bf16 v[128:131], v[132:135], v[108:111], v[128:131]
	v_mfma_f32_16x16x32_bf16 v[136:139], v[132:135], v[8:11], v[136:139]
	v_mfma_f32_16x16x32_bf16 v[140:143], v[132:135], v[40:43], v[140:143]
	v_mfma_f32_16x16x32_bf16 v[176:179], v[132:135], v[72:75], v[176:179]
	v_mfma_f32_16x16x32_bf16 v[128:131], v[132:135], v[104:107], v[128:131]
	ds_read_b128 v[132:135], v187 offset:128
	ds_read_b128 v[180:183], v187 offset:4480
	s_waitcnt lgkmcnt(0)
	v_mfma_f32_16x16x32_bf16 v[140:143], v[180:183], v[48:51], v[140:143]
	v_mfma_f32_16x16x32_bf16 v[136:139], v[180:183], v[16:19], v[136:139]
	v_mfma_f32_16x16x32_bf16 v[140:143], v[132:135], v[52:55], v[140:143]
	v_mfma_f32_16x16x32_bf16 v[136:139], v[132:135], v[20:23], v[136:139]
	v_mfma_f32_16x16x32_bf16 v[204:207], v[132:135], v[48:51], v[140:143]
	v_mfma_f32_16x16x32_bf16 v[140:143], v[180:183], v[80:83], v[176:179]
	v_mfma_f32_16x16x32_bf16 v[128:131], v[180:183], v[112:115], v[128:131]
	ds_read_b128 v[180:183], v187 offset:192
	ds_read_b128 v[208:211], v187 offset:4544
	v_mfma_f32_16x16x32_bf16 v[136:139], v[132:135], v[16:19], v[136:139]
	v_mfma_f32_16x16x32_bf16 v[140:143], v[132:135], v[84:87], v[140:143]
	v_mfma_f32_16x16x32_bf16 v[128:131], v[132:135], v[116:119], v[128:131]
	v_mfma_f32_16x16x32_bf16 v[176:179], v[132:135], v[80:83], v[140:143]
	v_mfma_f32_16x16x32_bf16 v[128:131], v[132:135], v[112:115], v[128:131]
	s_waitcnt lgkmcnt(0)
	v_mfma_f32_16x16x32_bf16 v[132:135], v[208:211], v[24:27], v[136:139]
	v_mfma_f32_16x16x32_bf16 v[132:135], v[180:183], v[28:31], v[132:135]
	v_mfma_f32_16x16x32_bf16 v[140:143], v[180:183], v[24:27], v[132:135]
	v_mfma_f32_16x16x32_bf16 v[132:135], v[208:211], v[56:59], v[204:207]
	v_mfma_f32_16x16x32_bf16 v[132:135], v[180:183], v[60:63], v[132:135]
	v_mfma_f32_16x16x32_bf16 v[136:139], v[180:183], v[56:59], v[132:135]
	v_mfma_f32_16x16x32_bf16 v[132:135], v[208:211], v[88:91], v[176:179]
	v_mfma_f32_16x16x32_bf16 v[128:131], v[208:211], v[120:123], v[128:131]
	v_mfma_f32_16x16x32_bf16 v[132:135], v[180:183], v[92:95], v[132:135]
	v_mfma_f32_16x16x32_bf16 v[128:131], v[180:183], v[124:127], v[128:131]
	v_mfma_f32_16x16x32_bf16 v[132:135], v[180:183], v[88:91], v[132:135]
	v_mfma_f32_16x16x32_bf16 v[128:131], v[180:183], v[120:123], v[128:131]
	s_and_saveexec_b64 s[0:1], s[14:15]
	s_cbranch_execz .LBB0_477
	ds_write_b32 v199, v140
	s_or_b64 exec, exec, s[0:1]
	s_and_saveexec_b64 s[0:1], s[16:17]
	s_cbranch_execnz .LBB0_478
